# chain<0> next-chunk prefetch re-ordered (a1, V rows, k) with relaxed in-order vmcnt waits; on top of cb_scan move + pipelined chain<0> state update
# baseline (speedup 1.0000x reference)
; __device__ __forceinline__ int crow(int r,int hi){return (r&3)+8*(r>>2)+4*hi;}
; __device__ __forceinline__ int crow(int r, int hi) { return (r & 3) + 8 * (r >> 2) + 4 * hi; }
; #define GBAR() asm volatile("s_waitcnt lgkmcnt(0)\n\ts_barrier" ::: "memory")
; #define lane lane_id_asm()
; template <int MODE> __device__ __forceinline__ void chain(int b, int h, int seg, float* __restrict__ SLOC, float* __restrict__ DTOT, const bf16_t* __restrict__ QB, const bf16_t* __restrict__ KB, const bf16_t* __restrict__ VB, bf16_t* __restrict__ OB, const bf16_t* __restrict__ RB, const float* __res ...
;     ...
;     f32x16 S[4];
; #pragma unroll
;     for (int i = 0; i < 4; ++i) S[i] = f32x16{};
;     const long row00 = (long)b * TSEQ + (long)seg * 1024;
;     float dt0 = 0.f, dt1 = 0.f;
;     if (MODE == 1) {
;         for (int g = 0; g < seg; ++g) { const float* sl = SLOC + ((size_t)((b * 4 + h) * 8 + g) * 128) * 256; const float* dd = DTOT + ((b * 4 + h) * 8 + g) * 128;
; #pragma unroll
;             for (int cb = 0; cb < 4; ++cb)
; #pragma unroll
;                 for (int r = 0; r < 16; ++r) { const int c = 32 * cb + crow(r, hi); S[cb][r] = __expf(dd[c]) * S[cb][r] + sl[(size_t)c * 256 + 32 * wid + r32]; } }
;     }
;     unsigned q2[8], k2[8]; float a1r0, a1r1; u32x4 vr[4];
;     const unsigned lo4 = (unsigned)lane * 4u, lov = (unsigned)(lane >> 5) * 2048u + (unsigned)(lane & 31) * 16u, lor = (unsigned)r32 * 2048u + (unsigned)hi * 8u;
;     ...
;     GLA_LOAD(row00);
;     GBAR();
;     const ldsp vtr0 = L + V_OFF + (8 * hi + ((lane & 15) >> 2)) * V_RS + (32 * wid + 16 * ((lane >> 4) & 1) + 4 * (lane & 3)) * 2;
.LBB0_486:
	s_or_b64 exec, exec, s[52:53]
	s_ashr_i32 s76, s58, 5
	s_bfe_u32 s60, s58, 0x30002
	s_and_b32 s13, s18, 3
	s_ashr_i32 s77, s76, 31
	s_lshl_b32 s30, s60, 24
	s_lshl_b32 s31, s13, 9
	s_lshl_b32 s34, s60, 19
	s_lshl_b32 s35, s60, 23
	s_lshl_b32 s36, s13, 8
	s_lshl_b32 s13, s60, 13
	s_lshl_b64 s[26:27], s[76:77], 10
	s_add_u32 s37, s26, s13
	s_addc_u32 s52, s27, 0
	s_add_u32 s26, s37, s11
	s_addc_u32 s27, s52, 0
	s_lshl_b64 s[28:29], s[26:27], 10
	s_add_u32 s13, s4, s28
	s_addc_u32 s28, s5, s29
	s_lshl_b32 s12, s12, 1
	s_add_u32 s12, s13, s12
	v_lshlrev_b32_e32 v98, 2, v3
	s_addc_u32 s13, s28, 0
	v_lshl_add_u64 v[10:11], s[12:13], 0, v[98:99]
	s_mov_b64 s[12:13], 0x1b500000
	v_lshl_add_u64 v[12:13], v[10:11], 0, s[12:13]
	s_mov_b32 s12, 0x1b501000
	v_add_co_u32_e32 v10, vcc, s12, v10
	s_lshl_b64 s[12:13], s[26:27], 6
	s_add_u32 s12, s68, s12
	v_addc_co_u32_e32 v11, vcc, 0, v11, vcc
	s_addc_u32 s13, s69, s13
	global_load_dword v112, v[12:13], off offset:1024
	global_load_dword v113, v[12:13], off offset:2048
	global_load_dword v115, v[12:13], off offset:3072
	global_load_dword v114, v[10:11], off offset:-4096
	global_load_dword v116, v[10:11], off
	global_load_dword v117, v[10:11], off offset:1024
	global_load_dword v118, v[10:11], off offset:2048
	global_load_dword v119, v[10:11], off offset:3072
	v_lshl_add_u64 v[10:11], s[12:13], 0, v[98:99]
	s_mov_b64 s[12:13], 0x2800000
	v_lshl_add_u64 v[12:13], v[10:11], 0, s[12:13]
	s_mov_b32 s12, 0x2800000
	v_add_co_u32_e32 v10, vcc, s12, v10
	v_readlane_b32 s12, v245, 53
	s_add_u32 s12, s37, s12
	s_addc_u32 s13, s52, 0
	v_and_b32_e32 v101, 31, v6
	s_lshl_b64 s[12:13], s[12:13], 11
	v_lshrrev_b32_e32 v111, 5, v3
	v_lshlrev_b32_e32 v5, 4, v101
	s_add_u32 s12, s78, s12
	v_lshl_or_b32 v8, v111, 11, v5
	s_addc_u32 s13, s79, s13
	v_mov_b32_e32 v5, v99
	v_lshl_add_u64 v[4:5], v[4:5], 1, s[12:13]
	v_mov_b32_e32 v9, v99
	v_addc_co_u32_e32 v11, vcc, 0, v11, vcc
	v_lshl_add_u64 v[4:5], v[4:5], 0, v[8:9]
	s_mov_b32 s12, 0x1f600000
	global_load_dword v120, v[10:11], off
	global_load_dword v121, v[12:13], off offset:256
	v_add_co_u32_e32 v10, vcc, s12, v4
	s_mov_b32 s12, 0x1f608000
	s_nop 0
	v_addc_co_u32_e32 v11, vcc, 0, v5, vcc
	v_add_co_u32_e32 v12, vcc, s12, v4
	s_mov_b32 s12, 0x1f610000
	s_nop 0
	v_addc_co_u32_e32 v13, vcc, 0, v5, vcc
	global_load_dwordx4 v[66:69], v[10:11], off
	global_load_dwordx4 v[70:73], v[12:13], off
	v_add_co_u32_e32 v10, vcc, s12, v4
	s_mov_b32 s12, 0x1f618000
	s_nop 0
	v_addc_co_u32_e32 v11, vcc, 0, v5, vcc
	v_add_co_u32_e32 v4, vcc, s12, v4
	v_readlane_b32 s12, v246, 53
	s_nop 0
	v_addc_co_u32_e32 v5, vcc, 0, v5, vcc
	global_load_dwordx4 v[74:77], v[10:11], off
	global_load_dwordx4 v[78:81], v[4:5], off
	v_lshlrev_b32_e32 v10, 2, v6
	v_bfe_u32 v4, v6, 2, 2
	v_and_b32_e32 v5, 16, v6
	v_and_b32_e32 v10, 12, v10
	v_lshl_or_b32 v4, v111, 3, v4
	v_or3_b32 v5, v5, v10, s12
	v_mul_u32_u24_e32 v4, 0x240, v4
	v_lshlrev_b32_e32 v5, 1, v5
	s_movk_i32 s12, 0x100
	v_add3_u32 v122, s12, v4, v5
	s_mov_b32 s12, 0x19e00
	v_lshlrev_b32_e32 v100, 2, v7
	s_addk_i32 s12, 0x100
	v_readlane_b32 s13, v246, 54
	v_add_u32_e32 v124, s12, v100
	v_readlane_b32 s12, v245, 54
	s_add_u32 s26, s78, s6
	s_addc_u32 s27, s79, s7
	v_add_u32_e32 v125, s12, v100
	s_lshl_b64 s[12:13], s[76:77], 21
	s_add_u32 s12, s30, s12
	s_addc_u32 s13, 0, s13
	s_or_b32 s12, s12, s31
	s_add_u32 s12, s26, s12
	s_addc_u32 s13, s27, s13
	s_add_u32 s26, s68, s8
	v_lshl_add_u64 v[106:107], s[12:13], 0, v[8:9]
	s_addc_u32 s27, s69, s9
	s_lshl_b64 s[12:13], s[76:77], 16
	s_add_u32 s12, s34, s12
	s_addc_u32 s13, 0, s13
	s_add_u32 s78, s26, s12
	s_addc_u32 s79, s27, s13
	s_add_u32 s12, s4, s14
	v_lshlrev_b32_e32 v5, 4, v111
	s_addc_u32 s13, s5, s15
	s_lshl_b64 s[4:5], s[76:77], 20
	v_lshlrev_b32_e32 v4, 4, v6
	v_add_u32_e32 v128, 0x100, v5
	v_lshrrev_b32_e32 v5, 5, v2
	v_add_u32_e32 v6, 0x200, v2
	v_add_u32_e32 v7, 0x400, v2
	v_add_u32_e32 v2, 0x600, v2
	s_add_u32 s4, s35, s4
	s_waitcnt lgkmcnt(0)
	s_barrier
	v_and_b32_e32 v4, 0x1f0, v4
	v_lshrrev_b32_e32 v6, 5, v6
	v_lshrrev_b32_e32 v7, 5, v7
	v_lshrrev_b32_e32 v2, 5, v2
	s_addc_u32 s5, 0, s5
	s_or_b32 s4, s4, s36
	v_add_u32_e32 v4, 0x100, v4
	v_mul_u32_u24_e32 v3, 0x120, v3
	v_mul_lo_u32 v5, v5, s22
	v_mul_lo_u32 v6, v6, s22
	v_mul_lo_u32 v7, v7, s22
	v_mul_lo_u32 v2, v2, s22
	v_mul_u32_u24_e32 v10, 0x90, v101
	s_add_u32 s80, s12, s4
	v_mov_b32_e32 v50, 0
	v_add_u32_e32 v123, 0xd000, v122
	v_add_u32_e32 v126, s23, v100
	v_add_u32_e32 v127, s24, v100
	s_addc_u32 s81, s13, s5
	s_mov_b64 s[82:83], 0
	v_add_u32_e32 v129, v4, v5
	v_add_u32_e32 v130, v4, v6
	v_add_u32_e32 v131, v4, v7
	v_add_u32_e32 v132, v4, v2
	v_add_u32_e32 v133, s19, v3
	v_add_u32_e32 v134, v128, v10
	v_mov_b32_e32 v51, v50
	v_mov_b32_e32 v52, v50
	v_mov_b32_e32 v53, v50
	v_mov_b32_e32 v54, v50
	v_mov_b32_e32 v55, v50
	v_mov_b32_e32 v56, v50
	v_mov_b32_e32 v57, v50
	v_mov_b32_e32 v58, v50
	v_mov_b32_e32 v59, v50
	v_mov_b32_e32 v60, v50
	v_mov_b32_e32 v61, v50
	v_mov_b32_e32 v62, v50
	v_mov_b32_e32 v63, v50
	v_mov_b32_e32 v64, v50
	v_mov_b32_e32 v65, v50
	v_mov_b32_e32 v34, v50
	v_mov_b32_e32 v35, v50
	v_mov_b32_e32 v36, v50
	v_mov_b32_e32 v37, v50
	v_mov_b32_e32 v38, v50
	v_mov_b32_e32 v39, v50
	v_mov_b32_e32 v40, v50
	v_mov_b32_e32 v41, v50
	v_mov_b32_e32 v42, v50
	v_mov_b32_e32 v43, v50
	v_mov_b32_e32 v44, v50
	v_mov_b32_e32 v45, v50
	v_mov_b32_e32 v46, v50
	v_mov_b32_e32 v47, v50
	v_mov_b32_e32 v48, v50
	v_mov_b32_e32 v49, v50
	v_mov_b32_e32 v18, v50
	v_mov_b32_e32 v19, v50
	v_mov_b32_e32 v20, v50
	v_mov_b32_e32 v21, v50
	v_mov_b32_e32 v22, v50
	v_mov_b32_e32 v23, v50
	v_mov_b32_e32 v24, v50
	v_mov_b32_e32 v25, v50
	v_mov_b32_e32 v26, v50
	v_mov_b32_e32 v27, v50
	v_mov_b32_e32 v28, v50
	v_mov_b32_e32 v29, v50
	v_mov_b32_e32 v30, v50
	v_mov_b32_e32 v31, v50
	v_mov_b32_e32 v32, v50
	v_mov_b32_e32 v33, v50
	v_mov_b32_e32 v2, v50
	v_mov_b32_e32 v3, v50
	v_mov_b32_e32 v4, v50
	v_mov_b32_e32 v5, v50
	v_mov_b32_e32 v6, v50
	v_mov_b32_e32 v7, v50
	v_mov_b32_e32 v8, v50
	v_mov_b32_e32 v9, v50
	v_mov_b32_e32 v10, v50
	v_mov_b32_e32 v11, v50
	v_mov_b32_e32 v12, v50
	v_mov_b32_e32 v13, v50
	v_mov_b32_e32 v14, v50
	v_mov_b32_e32 v15, v50
	v_mov_b32_e32 v16, v50
	v_mov_b32_e32 v17, v50
	v_mov_b32_e32 v104, v50
	v_mov_b32_e32 v105, v50
	s_waitcnt vmcnt(0)
	s_branch .LBB0_488

; #define GLDS __attribute__((address_space(3)))
; template <int MODE> __device__ __forceinline__ void chain(int b, int h, int seg, float* __restrict__ SLOC, float* __restrict__ DTOT, const bf16_t* __restrict__ QB, const bf16_t* __restrict__ KB, const bf16_t* __restrict__ VB, bf16_t* __restrict__ OB, const bf16_t* __restrict__ RB, const float* __res ...
;     ...
;         {
;             float z0[8], z1[8];
; #pragma unroll
;             for (int i = 0; i < 8; ++i) { z0[i] = ba0; z1[i] = ba1; }
; #pragma unroll
;             for (int r = 0; r < 16; ++r) { const f32x2 w = *(const GLDS f32x2*)(W2 + r * 128 + c0);
; #pragma unroll
;                 for (int i = 0; i < 8; ++i) { const int e = i * 16 + r; const float a = __uint_as_float(__builtin_amdgcn_readlane(__float_as_uint(e < 64 ? a1r0 : a1r1), e & 63)); z0[i] += a * w.x; z1[i] += a * w.y; } }
.LBB0_488:
	ds_read2st64_b64 v[82:85], v124 offset1:1
	ds_read2st64_b64 v[86:89], v124 offset0:2 offset1:3
	s_waitcnt vmcnt(12)
	v_readlane_b32 s4, v120, 0
	v_readlane_b32 s5, v120, 16
	v_readlane_b32 s12, v120, 22
	s_waitcnt lgkmcnt(1)
	v_fma_f32 v90, s4, v82, v102
	v_fma_f32 v91, s4, v83, v103
	v_readlane_b32 s4, v120, 32
	v_fma_f32 v92, s5, v82, v102
	v_fma_f32 v93, s5, v83, v103
	v_fma_f32 v94, s4, v82, v102
	v_fma_f32 v95, s4, v83, v103
	v_readlane_b32 s4, v120, 48
	v_readlane_b32 s5, v120, 7
	v_readlane_b32 s13, v120, 23
	v_fma_f32 v96, s4, v82, v102
	v_fma_f32 v97, s4, v83, v103
	v_readlane_b32 s4, v121, 0
	v_readlane_b32 s26, v120, 38
	v_readlane_b32 s27, v120, 39
	v_fma_f32 v108, s4, v82, v102
	v_fma_f32 v109, s4, v83, v103
	v_readlane_b32 s4, v121, 16
	v_readlane_b32 s28, v120, 54
	v_readlane_b32 s29, v120, 55
	v_fma_f32 v135, s4, v82, v102
	v_fma_f32 v136, s4, v83, v103
	v_readlane_b32 s4, v121, 32
	v_readlane_b32 s30, v121, 6
	v_readlane_b32 s31, v121, 7
	v_fma_f32 v137, s4, v82, v102
	v_fma_f32 v138, s4, v83, v103
	v_readlane_b32 s4, v121, 48
	v_readlane_b32 s34, v121, 22
	v_readlane_b32 s35, v121, 23
	v_fma_f32 v139, s4, v82, v102
	v_fma_f32 v140, s4, v83, v103
	v_readlane_b32 s4, v120, 1
	v_readlane_b32 s36, v121, 38
	v_readlane_b32 s52, v121, 54
	v_fmac_f32_e32 v90, s4, v84
	v_fmac_f32_e32 v91, s4, v85
	v_readlane_b32 s4, v120, 17
	v_readlane_b32 s37, v121, 39
	v_readlane_b32 s53, v121, 55
	v_fmac_f32_e32 v92, s4, v84
	v_fmac_f32_e32 v93, s4, v85
	v_readlane_b32 s4, v120, 33
	v_readlane_b32 vcc_lo, v120, 24
	v_readlane_b32 vcc_hi, v120, 25
	v_fmac_f32_e32 v94, s4, v84
	v_fmac_f32_e32 v95, s4, v85
	v_readlane_b32 s4, v120, 49
	v_readlane_b32 s92, v120, 40
	v_readlane_b32 s93, v120, 41
	v_fmac_f32_e32 v96, s4, v84
	v_fmac_f32_e32 v97, s4, v85
	v_readlane_b32 s4, v121, 1
	v_readlane_b32 s68, v120, 56
	v_readlane_b32 s69, v120, 57
	v_fmac_f32_e32 v108, s4, v84
	v_fmac_f32_e32 v109, s4, v85
	v_readlane_b32 s4, v121, 17
	v_readlane_b32 s56, v121, 8
	v_readlane_b32 s57, v121, 9
	v_fmac_f32_e32 v135, s4, v84
	v_fmac_f32_e32 v136, s4, v85
	v_readlane_b32 s4, v121, 33
	v_readlane_b32 s54, v121, 24
	v_readlane_b32 s55, v121, 25
	v_fmac_f32_e32 v137, s4, v84
	v_fmac_f32_e32 v138, s4, v85
	v_readlane_b32 s4, v121, 49
	s_nop 1
	v_fmac_f32_e32 v139, s4, v84
	v_fmac_f32_e32 v140, s4, v85
	v_readlane_b32 s4, v120, 2
	ds_read2st64_b64 v[82:85], v124 offset0:4 offset1:5
	s_waitcnt lgkmcnt(1)
	v_fmac_f32_e32 v90, s4, v86
	v_fmac_f32_e32 v91, s4, v87
	v_readlane_b32 s4, v120, 18
	s_nop 1
	v_fmac_f32_e32 v92, s4, v86
	v_fmac_f32_e32 v93, s4, v87
	v_readlane_b32 s4, v120, 34
	s_nop 1
	v_fmac_f32_e32 v94, s4, v86
	v_fmac_f32_e32 v95, s4, v87
	v_readlane_b32 s4, v120, 50
	s_nop 1
	v_fmac_f32_e32 v96, s4, v86
	v_fmac_f32_e32 v97, s4, v87
	v_readlane_b32 s4, v121, 2
	s_nop 1
	v_fmac_f32_e32 v108, s4, v86
	v_fmac_f32_e32 v109, s4, v87
	v_readlane_b32 s4, v121, 18
	s_nop 1
	v_fmac_f32_e32 v135, s4, v86
	v_fmac_f32_e32 v136, s4, v87
	v_readlane_b32 s4, v121, 34
	s_nop 1
	v_fmac_f32_e32 v137, s4, v86
	v_fmac_f32_e32 v138, s4, v87
	v_readlane_b32 s4, v121, 50
	s_nop 1
	v_fmac_f32_e32 v139, s4, v86
	v_fmac_f32_e32 v140, s4, v87
	v_readlane_b32 s4, v120, 3
	s_nop 1
	v_fmac_f32_e32 v90, s4, v88
	v_fmac_f32_e32 v91, s4, v89
	v_readlane_b32 s4, v120, 19
	s_nop 1
	v_fmac_f32_e32 v92, s4, v88
	v_fmac_f32_e32 v93, s4, v89
	v_readlane_b32 s4, v120, 35
	s_nop 1
	v_fmac_f32_e32 v94, s4, v88
	v_fmac_f32_e32 v95, s4, v89
	v_readlane_b32 s4, v120, 51
	s_nop 1
	v_fmac_f32_e32 v96, s4, v88
	v_fmac_f32_e32 v97, s4, v89
	v_readlane_b32 s4, v121, 3
	s_nop 1
	v_fmac_f32_e32 v108, s4, v88
	v_fmac_f32_e32 v109, s4, v89
	v_readlane_b32 s4, v121, 19
	s_nop 1
	v_fmac_f32_e32 v135, s4, v88
	v_fmac_f32_e32 v136, s4, v89
	v_readlane_b32 s4, v121, 35
	s_nop 1
	v_fmac_f32_e32 v137, s4, v88
	v_fmac_f32_e32 v138, s4, v89
	v_readlane_b32 s4, v121, 51
	s_nop 1
	v_fmac_f32_e32 v139, s4, v88
	v_fmac_f32_e32 v140, s4, v89
	v_readlane_b32 s4, v120, 4
	ds_read2st64_b64 v[86:89], v124 offset0:6 offset1:7
	s_waitcnt lgkmcnt(1)
	v_fmac_f32_e32 v90, s4, v82
	v_fmac_f32_e32 v91, s4, v83
	v_readlane_b32 s4, v120, 20
	s_nop 1
	v_fmac_f32_e32 v92, s4, v82
	v_fmac_f32_e32 v93, s4, v83
	v_readlane_b32 s4, v120, 36
	s_nop 1
	v_fmac_f32_e32 v94, s4, v82
	v_fmac_f32_e32 v95, s4, v83
	v_readlane_b32 s4, v120, 52
	s_nop 1
	v_fmac_f32_e32 v96, s4, v82
	v_fmac_f32_e32 v97, s4, v83
	v_readlane_b32 s4, v121, 4
	s_nop 1
	v_fmac_f32_e32 v108, s4, v82
	v_fmac_f32_e32 v109, s4, v83
	v_readlane_b32 s4, v121, 20
	s_nop 1
	v_fmac_f32_e32 v135, s4, v82
	v_fmac_f32_e32 v136, s4, v83
	v_readlane_b32 s4, v121, 36
	s_nop 1
	v_fmac_f32_e32 v137, s4, v82
	v_fmac_f32_e32 v138, s4, v83
	v_readlane_b32 s4, v121, 52
	s_nop 1
	v_fmac_f32_e32 v139, s4, v82
	v_fmac_f32_e32 v140, s4, v83
	v_readlane_b32 s4, v120, 5
	s_waitcnt lgkmcnt(0)
; #define GLDS __attribute__((address_space(3)))
; template <int MODE> __device__ __forceinline__ void chain(int b, int h, int seg, float* __restrict__ SLOC, float* __restrict__ DTOT, const bf16_t* __restrict__ QB, const bf16_t* __restrict__ KB, const bf16_t* __restrict__ VB, bf16_t* __restrict__ OB, const bf16_t* __restrict__ RB, const float* __res ...
;     ...
;             for (int r = 0; r < 16; ++r) { const f32x2 w = *(const GLDS f32x2*)(W2 + r * 128 + c0);
; #pragma unroll
;                 for (int i = 0; i < 8; ++i) { const int e = i * 16 + r; const float a = __uint_as_float(__builtin_amdgcn_readlane(__float_as_uint(e < 64 ? a1r0 : a1r1), e & 63)); z0[i] += a * w.x; z1[i] += a * w.y; } }
	v_mov_b32_e32 v82, v86
	v_mov_b32_e32 v83, v88
	v_fmac_f32_e32 v90, s4, v84
	v_fmac_f32_e32 v91, s4, v85
	v_readlane_b32 s4, v120, 21
	v_mov_b32_e32 v88, v87
	s_nop 0
	v_fmac_f32_e32 v92, s4, v84
	v_fmac_f32_e32 v93, s4, v85
	v_readlane_b32 s4, v120, 37
	s_nop 1
	v_fmac_f32_e32 v94, s4, v84
	v_fmac_f32_e32 v95, s4, v85
	v_readlane_b32 s4, v120, 53
	s_nop 1
	v_fmac_f32_e32 v96, s4, v84
	v_fmac_f32_e32 v97, s4, v85
	v_readlane_b32 s4, v121, 5
	s_nop 1
	v_fmac_f32_e32 v108, s4, v84
	v_fmac_f32_e32 v109, s4, v85
	v_readlane_b32 s4, v121, 21
	s_nop 1
	v_fmac_f32_e32 v135, s4, v84
	v_fmac_f32_e32 v136, s4, v85
	v_readlane_b32 s4, v121, 37
	s_nop 1
	v_fmac_f32_e32 v137, s4, v84
	v_fmac_f32_e32 v138, s4, v85
	v_readlane_b32 s4, v121, 53
	s_nop 1
	v_fmac_f32_e32 v139, s4, v84
	v_fmac_f32_e32 v140, s4, v85
	v_readlane_b32 s4, v120, 6
	s_nop 1
	v_pk_mul_f32 v[84:85], v[82:83], s[4:5]
	s_nop 0
	v_add_f32_e32 v84, v90, v84
	v_add_f32_e32 v141, v84, v85
	v_pk_mul_f32 v[84:85], v[88:89], s[4:5]
	v_readlane_b32 s4, v121, 56
	v_add_f32_e32 v84, v91, v84
	v_add_f32_e32 v142, v84, v85
	v_pk_mul_f32 v[84:85], v[82:83], s[12:13]
	v_readlane_b32 s5, v121, 57
	v_add_f32_e32 v84, v92, v84
	v_add_f32_e32 v143, v84, v85
	v_pk_mul_f32 v[84:85], v[88:89], s[12:13]
	v_readlane_b32 s12, v120, 8
	v_add_f32_e32 v84, v93, v84
	v_add_f32_e32 v144, v84, v85
	v_pk_mul_f32 v[84:85], v[82:83], s[26:27]
	v_readlane_b32 s13, v120, 9
	v_add_f32_e32 v84, v94, v84
	v_add_f32_e32 v94, v84, v85
	v_pk_mul_f32 v[84:85], v[88:89], s[26:27]
	v_readlane_b32 s26, v120, 42
	v_add_f32_e32 v84, v95, v84
	v_add_f32_e32 v95, v84, v85
	v_pk_mul_f32 v[84:85], v[82:83], s[28:29]
	v_readlane_b32 s27, v120, 43
	v_add_f32_e32 v84, v96, v84
	v_add_f32_e32 v96, v84, v85
	v_pk_mul_f32 v[84:85], v[88:89], s[28:29]
	v_readlane_b32 s28, v120, 58
	v_add_f32_e32 v84, v97, v84
	v_add_f32_e32 v97, v84, v85
	v_pk_mul_f32 v[84:85], v[82:83], s[30:31]
	v_readlane_b32 s29, v120, 59
	v_add_f32_e32 v84, v108, v84
	v_add_f32_e32 v108, v84, v85
	v_pk_mul_f32 v[84:85], v[88:89], s[30:31]
	v_readlane_b32 s30, v121, 10
	v_add_f32_e32 v84, v109, v84
	v_add_f32_e32 v109, v84, v85
	v_pk_mul_f32 v[84:85], v[82:83], s[34:35]
	v_readlane_b32 s31, v121, 11
	v_add_f32_e32 v84, v135, v84
	v_add_f32_e32 v135, v84, v85
	v_pk_mul_f32 v[84:85], v[88:89], s[34:35]
	v_readlane_b32 s34, v121, 26
	v_add_f32_e32 v84, v136, v84
	v_add_f32_e32 v136, v84, v85
	v_pk_mul_f32 v[84:85], v[82:83], s[36:37]
	v_pk_mul_f32 v[82:83], v[82:83], s[52:53]
	v_add_f32_e32 v84, v137, v84
	v_add_f32_e32 v82, v139, v82
	v_add_f32_e32 v137, v84, v85
	v_pk_mul_f32 v[84:85], v[88:89], s[36:37]
	v_add_f32_e32 v139, v82, v83
	v_pk_mul_f32 v[82:83], v[88:89], s[52:53]
	v_add_f32_e32 v84, v138, v84
	v_add_f32_e32 v82, v140, v82
	v_add_f32_e32 v138, v84, v85
	v_add_f32_e32 v140, v82, v83
	ds_read2st64_b64 v[82:85], v124 offset0:8 offset1:9
	ds_read2st64_b64 v[86:89], v124 offset0:10 offset1:11
	v_readlane_b32 s52, v121, 40
	v_readlane_b32 s53, v121, 41
	v_readlane_b32 s35, v121, 27
	s_waitcnt lgkmcnt(1)
	v_mov_b32_e32 v90, v82
	v_mov_b32_e32 v91, v84
	v_pk_mul_f32 v[92:93], v[90:91], s[12:13]
	v_mov_b32_e32 v84, v83
	v_add_f32_e32 v82, v141, v92
	v_add_f32_e32 v92, v82, v93
	v_pk_mul_f32 v[82:83], v[84:85], s[12:13]
	v_readlane_b32 s12, v120, 26
	v_add_f32_e32 v82, v142, v82
	v_add_f32_e32 v93, v82, v83
	v_pk_mul_f32 v[82:83], v[90:91], vcc
	v_readlane_b32 s13, v120, 27
	v_add_f32_e32 v82, v143, v82
	v_add_f32_e32 v141, v82, v83
	v_pk_mul_f32 v[82:83], v[84:85], vcc
	v_readlane_b32 s36, v121, 42
	v_add_f32_e32 v82, v144, v82
	v_add_f32_e32 v142, v82, v83
	v_pk_mul_f32 v[82:83], v[90:91], s[92:93]
	v_readlane_b32 s37, v121, 43
	v_add_f32_e32 v82, v94, v82
	v_add_f32_e32 v94, v82, v83
	v_pk_mul_f32 v[82:83], v[84:85], s[92:93]
	v_readlane_b32 vcc_lo, v120, 28
	v_add_f32_e32 v82, v95, v82
	v_add_f32_e32 v95, v82, v83
	v_pk_mul_f32 v[82:83], v[90:91], s[68:69]
	v_readlane_b32 vcc_hi, v120, 29
	v_add_f32_e32 v82, v96, v82
	v_add_f32_e32 v96, v82, v83
	v_pk_mul_f32 v[82:83], v[84:85], s[68:69]
	v_readlane_b32 s92, v120, 44
	v_add_f32_e32 v82, v97, v82
	v_add_f32_e32 v97, v82, v83
	v_pk_mul_f32 v[82:83], v[90:91], s[56:57]
	v_readlane_b32 s93, v120, 45
	v_add_f32_e32 v82, v108, v82
	v_add_f32_e32 v108, v82, v83
	v_pk_mul_f32 v[82:83], v[84:85], s[56:57]
	v_readlane_b32 s68, v120, 60
	v_add_f32_e32 v82, v109, v82
	v_add_f32_e32 v109, v82, v83
	v_pk_mul_f32 v[82:83], v[90:91], s[54:55]
	v_readlane_b32 s69, v120, 61
	v_add_f32_e32 v82, v135, v82
	v_add_f32_e32 v135, v82, v83
	v_pk_mul_f32 v[82:83], v[84:85], s[54:55]
	v_readlane_b32 s56, v121, 12
	v_add_f32_e32 v82, v136, v82
	v_add_f32_e32 v136, v82, v83
	v_pk_mul_f32 v[82:83], v[90:91], s[52:53]
	v_readlane_b32 s57, v121, 13
	v_add_f32_e32 v82, v137, v82
	v_add_f32_e32 v137, v82, v83
	v_pk_mul_f32 v[82:83], v[84:85], s[52:53]
	v_readlane_b32 s52, v121, 58
	v_add_f32_e32 v82, v138, v82
	v_add_f32_e32 v138, v82, v83
	v_pk_mul_f32 v[82:83], v[90:91], s[4:5]
	v_readlane_b32 s53, v121, 59
	v_add_f32_e32 v82, v139, v82
	v_add_f32_e32 v90, v82, v83
	v_pk_mul_f32 v[82:83], v[84:85], s[4:5]
	v_readlane_b32 s4, v120, 10
	v_add_f32_e32 v82, v140, v82
	v_add_f32_e32 v91, v82, v83
	v_readlane_b32 s5, v120, 11
	s_waitcnt lgkmcnt(0)
; #define GLDS __attribute__((address_space(3)))
; template <int MODE> __device__ __forceinline__ void chain(int b, int h, int seg, float* __restrict__ SLOC, float* __restrict__ DTOT, const bf16_t* __restrict__ QB, const bf16_t* __restrict__ KB, const bf16_t* __restrict__ VB, bf16_t* __restrict__ OB, const bf16_t* __restrict__ RB, const float* __res ...
;     ...
;             for (int r = 0; r < 16; ++r) { const f32x2 w = *(const GLDS f32x2*)(W2 + r * 128 + c0);
; #pragma unroll
;                 for (int i = 0; i < 8; ++i) { const int e = i * 16 + r; const float a = __uint_as_float(__builtin_amdgcn_readlane(__float_as_uint(e < 64 ? a1r0 : a1r1), e & 63)); z0[i] += a * w.x; z1[i] += a * w.y; } }
	v_mov_b32_e32 v82, v86
	v_mov_b32_e32 v83, v88
	v_pk_mul_f32 v[84:85], v[82:83], s[4:5]
	v_mov_b32_e32 v88, v87
	v_add_f32_e32 v84, v92, v84
	v_add_f32_e32 v139, v84, v85
	v_pk_mul_f32 v[84:85], v[88:89], s[4:5]
	v_readlane_b32 s54, v121, 28
	v_add_f32_e32 v84, v93, v84
	v_add_f32_e32 v140, v84, v85
	v_pk_mul_f32 v[84:85], v[82:83], s[12:13]
	v_readlane_b32 s55, v121, 29
	v_add_f32_e32 v84, v141, v84
	v_add_f32_e32 v141, v84, v85
	v_pk_mul_f32 v[84:85], v[88:89], s[12:13]
	v_readlane_b32 s12, v120, 12
	v_add_f32_e32 v84, v142, v84
	v_add_f32_e32 v142, v84, v85
	v_pk_mul_f32 v[84:85], v[82:83], s[26:27]
	v_readlane_b32 s13, v120, 13
	v_add_f32_e32 v84, v94, v84
	v_add_f32_e32 v94, v84, v85
	v_pk_mul_f32 v[84:85], v[88:89], s[26:27]
	v_readlane_b32 s4, v121, 60
	v_add_f32_e32 v84, v95, v84
	v_add_f32_e32 v95, v84, v85
	v_pk_mul_f32 v[84:85], v[82:83], s[28:29]
	v_readlane_b32 s5, v121, 61
	v_add_f32_e32 v84, v96, v84
	v_add_f32_e32 v96, v84, v85
	v_pk_mul_f32 v[84:85], v[88:89], s[28:29]
	v_readlane_b32 s26, v120, 46
	v_add_f32_e32 v84, v97, v84
	v_add_f32_e32 v97, v84, v85
	v_pk_mul_f32 v[84:85], v[82:83], s[30:31]
	v_readlane_b32 s27, v120, 47
	v_add_f32_e32 v84, v108, v84
	v_add_f32_e32 v108, v84, v85
	v_pk_mul_f32 v[84:85], v[88:89], s[30:31]
	v_readlane_b32 s28, v120, 62
	v_add_f32_e32 v84, v109, v84
	v_add_f32_e32 v109, v84, v85
	v_pk_mul_f32 v[84:85], v[82:83], s[34:35]
	v_readlane_b32 s29, v120, 63
	v_add_f32_e32 v84, v135, v84
	v_add_f32_e32 v135, v84, v85
	v_pk_mul_f32 v[84:85], v[88:89], s[34:35]
	v_readlane_b32 s30, v121, 14
	v_add_f32_e32 v84, v136, v84
	v_add_f32_e32 v136, v84, v85
	v_pk_mul_f32 v[84:85], v[82:83], s[36:37]
	v_pk_mul_f32 v[82:83], v[82:83], s[52:53]
	v_add_f32_e32 v84, v137, v84
	v_add_f32_e32 v82, v90, v82
	v_add_f32_e32 v137, v84, v85
	v_pk_mul_f32 v[84:85], v[88:89], s[36:37]
	v_add_f32_e32 v143, v82, v83
	v_pk_mul_f32 v[82:83], v[88:89], s[52:53]
	v_add_f32_e32 v84, v138, v84
	v_add_f32_e32 v82, v91, v82
	v_add_f32_e32 v138, v84, v85
	v_add_f32_e32 v144, v82, v83
	ds_read2st64_b64 v[82:85], v124 offset0:12 offset1:13
	ds_read2st64_b64 v[86:89], v124 offset0:14 offset1:15
	v_readlane_b32 s52, v121, 44
	v_readlane_b32 s53, v121, 45
	v_readlane_b32 s31, v121, 15
	s_waitcnt lgkmcnt(1)
	v_mov_b32_e32 v90, v82
	v_mov_b32_e32 v91, v84
	v_pk_mul_f32 v[92:93], v[90:91], s[12:13]
	v_mov_b32_e32 v84, v83
	v_add_f32_e32 v82, v139, v92
	v_add_f32_e32 v92, v82, v93
	v_pk_mul_f32 v[82:83], v[84:85], s[12:13]
	v_readlane_b32 s12, v120, 30
	v_add_f32_e32 v82, v140, v82
	v_add_f32_e32 v93, v82, v83
	v_pk_mul_f32 v[82:83], v[90:91], vcc
	v_readlane_b32 s13, v120, 31
	v_add_f32_e32 v82, v141, v82
	v_add_f32_e32 v139, v82, v83
	v_pk_mul_f32 v[82:83], v[84:85], vcc
	v_readlane_b32 s34, v121, 30
	v_add_f32_e32 v82, v142, v82
	v_add_f32_e32 v140, v82, v83
	v_pk_mul_f32 v[82:83], v[90:91], s[92:93]
	v_readlane_b32 s35, v121, 31
	v_add_f32_e32 v82, v94, v82
	v_add_f32_e32 v94, v82, v83
	v_pk_mul_f32 v[82:83], v[84:85], s[92:93]
	v_readlane_b32 s36, v121, 46
	v_add_f32_e32 v82, v95, v82
	v_add_f32_e32 v95, v82, v83
	v_pk_mul_f32 v[82:83], v[90:91], s[68:69]
	v_readlane_b32 s37, v121, 47
	v_add_f32_e32 v82, v96, v82
	v_add_f32_e32 v96, v82, v83
	v_pk_mul_f32 v[82:83], v[84:85], s[68:69]
	s_nop 0
	v_add_f32_e32 v82, v97, v82
	v_add_f32_e32 v97, v82, v83
	v_pk_mul_f32 v[82:83], v[90:91], s[56:57]
	s_nop 0
	v_add_f32_e32 v82, v108, v82
	v_add_f32_e32 v108, v82, v83
	v_pk_mul_f32 v[82:83], v[84:85], s[56:57]
	s_nop 0
	v_add_f32_e32 v82, v109, v82
	v_add_f32_e32 v109, v82, v83
	v_pk_mul_f32 v[82:83], v[90:91], s[54:55]
	s_nop 0
	v_add_f32_e32 v82, v135, v82
	v_add_f32_e32 v135, v82, v83
	v_pk_mul_f32 v[82:83], v[84:85], s[54:55]
	s_nop 0
	v_add_f32_e32 v82, v136, v82
	v_add_f32_e32 v136, v82, v83
	v_pk_mul_f32 v[82:83], v[90:91], s[52:53]
	s_nop 0
	v_add_f32_e32 v82, v137, v82
	v_add_f32_e32 v137, v82, v83
	v_pk_mul_f32 v[82:83], v[84:85], s[52:53]
	v_readlane_b32 s52, v121, 62
	v_add_f32_e32 v82, v138, v82
	v_add_f32_e32 v138, v82, v83
	v_pk_mul_f32 v[82:83], v[90:91], s[4:5]
	v_readlane_b32 s53, v121, 63
	v_add_f32_e32 v82, v143, v82
	v_add_f32_e32 v90, v82, v83
	v_pk_mul_f32 v[82:83], v[84:85], s[4:5]
	v_readlane_b32 s4, v120, 14
	v_add_f32_e32 v82, v144, v82
	v_add_f32_e32 v91, v82, v83
	v_readlane_b32 s5, v120, 15
	s_waitcnt lgkmcnt(0)
; #define GLDS __attribute__((address_space(3)))
; __device__ __forceinline__ float logsig(float z) { return fminf(z, 0.f) - __logf(1.0f + __expf(-fabsf(z))); }
; template <int MODE> __device__ __forceinline__ void chain(int b, int h, int seg, float* __restrict__ SLOC, float* __restrict__ DTOT, const bf16_t* __restrict__ QB, const bf16_t* __restrict__ KB, const bf16_t* __restrict__ VB, bf16_t* __restrict__ OB, const bf16_t* __restrict__ RB, const float* __res ...
;     ...
;             for (int r = 0; r < 16; ++r) { const f32x2 w = *(const GLDS f32x2*)(W2 + r * 128 + c0);
; #pragma unroll
;                 for (int i = 0; i < 8; ++i) { const int e = i * 16 + r; const float a = __uint_as_float(__builtin_amdgcn_readlane(__float_as_uint(e < 64 ? a1r0 : a1r1), e & 63)); z0[i] += a * w.x; z1[i] += a * w.y; } }
;             float run0 = 0.f, run1 = 0.f;
; #pragma unroll
;             for (int i = 0; i < 8; ++i) { run0 += logsig(z0[i]) * 0.0625f; run1 += logsig(z1[i]) * 0.0625f; bl0[i] = run0; bl1[i] = run1; }
	v_mov_b32_e32 v82, v86
	v_mov_b32_e32 v83, v88
	v_pk_mul_f32 v[84:85], v[82:83], s[4:5]
	v_mov_b32_e32 v88, v87
	v_add_f32_e32 v84, v92, v84
	v_add_f32_e32 v86, v84, v85
	v_pk_mul_f32 v[84:85], v[88:89], s[4:5]
	s_nop 0
	v_add_f32_e32 v84, v93, v84
	v_add_f32_e32 v87, v84, v85
	v_pk_mul_f32 v[84:85], v[82:83], s[12:13]
	s_nop 0
	v_add_f32_e32 v84, v139, v84
	v_add_f32_e32 v92, v84, v85
	v_pk_mul_f32 v[84:85], v[88:89], s[12:13]
	s_nop 0
	v_add_f32_e32 v84, v140, v84
	v_add_f32_e32 v93, v84, v85
	v_pk_mul_f32 v[84:85], v[82:83], s[26:27]
	s_nop 0
	v_add_f32_e32 v84, v94, v84
	v_add_f32_e32 v94, v84, v85
	v_pk_mul_f32 v[84:85], v[88:89], s[26:27]
	s_nop 0
	v_add_f32_e32 v84, v95, v84
	v_add_f32_e32 v95, v84, v85
	v_pk_mul_f32 v[84:85], v[82:83], s[28:29]
	s_nop 0
	v_add_f32_e32 v84, v96, v84
	v_add_f32_e32 v96, v84, v85
	v_pk_mul_f32 v[84:85], v[88:89], s[28:29]
	s_nop 0
	v_add_f32_e32 v84, v97, v84
	v_add_f32_e32 v97, v84, v85
	v_pk_mul_f32 v[84:85], v[82:83], s[30:31]
	s_nop 0
	v_add_f32_e32 v84, v108, v84
	v_add_f32_e32 v108, v84, v85
	v_pk_mul_f32 v[84:85], v[88:89], s[30:31]
	s_nop 0
	v_add_f32_e32 v84, v109, v84
	v_add_f32_e32 v109, v84, v85
	v_pk_mul_f32 v[84:85], v[82:83], s[34:35]
	s_nop 0
	v_add_f32_e32 v84, v135, v84
	v_add_f32_e32 v135, v84, v85
	v_pk_mul_f32 v[84:85], v[88:89], s[34:35]
	v_mul_f32_e64 v140, |v135|, s25
	v_add_f32_e32 v84, v136, v84
	v_add_f32_e32 v139, v84, v85
	v_pk_mul_f32 v[84:85], v[82:83], s[36:37]
	v_pk_mul_f32 v[82:83], v[82:83], s[52:53]
	v_add_f32_e32 v84, v137, v84
	v_add_f32_e32 v142, v84, v85
	v_pk_mul_f32 v[84:85], v[88:89], s[36:37]
	v_add_f32_e32 v82, v90, v82
	v_add_f32_e32 v84, v138, v84
	v_add_f32_e32 v143, v84, v85
	v_mul_f32_e64 v84, |v86|, s25
	v_exp_f32_e32 v84, v84
	v_add_f32_e32 v146, v82, v83
	v_pk_mul_f32 v[82:83], v[88:89], s[52:53]
	v_mul_f32_e64 v89, |v93|, s25
	v_add_f32_e32 v84, 1.0, v84
	v_cmp_gt_f32_e32 vcc, s71, v84
	v_add_f32_e32 v82, v91, v82
	v_add_f32_e32 v147, v82, v83
	v_cndmask_b32_e64 v85, 0, 32, vcc
	v_ldexp_f32 v84, v84, v85
	v_log_f32_e32 v84, v84
	v_mul_f32_e64 v85, |v87|, s25
	v_exp_f32_e32 v85, v85
	v_min_f32_e32 v82, 0, v86
	v_mul_f32_e32 v83, 0x3f317217, v84
	v_fma_f32 v83, v84, s20, -v83
	v_fmac_f32_e32 v83, 0x3377d1cf, v84
	v_fmac_f32_e32 v83, 0x3f317217, v84
	v_cmp_lt_f32_e64 s[68:69], |v84|, s21
	v_exp_f32_e32 v89, v89
	v_mul_f32_e64 v91, |v94|, s25
	v_cndmask_b32_e64 v83, v84, v83, s[68:69]
	v_add_f32_e32 v84, 1.0, v85
	v_cmp_gt_f32_e64 s[68:69], s71, v84
	v_exp_f32_e32 v91, v91
	v_mul_f32_e64 v136, |v97|, s25
	v_cndmask_b32_e64 v85, 0, 32, s[68:69]
	v_ldexp_f32 v84, v84, v85
	v_log_f32_e32 v85, v84
	v_cndmask_b32_e32 v84, 0, v110, vcc
	v_sub_f32_e32 v84, v83, v84
	v_min_f32_e32 v83, 0, v87
	v_mul_f32_e64 v87, |v92|, s25
	v_mul_f32_e32 v86, 0x3f317217, v85
	v_exp_f32_e32 v87, v87
	v_fma_f32 v86, v85, s20, -v86
	v_fmac_f32_e32 v86, 0x3377d1cf, v85
	v_fmac_f32_e32 v86, 0x3f317217, v85
	v_cmp_lt_f32_e64 vcc, |v85|, s21
	v_exp_f32_e32 v136, v136
	v_mul_f32_e64 v137, |v108|, s25
	v_cndmask_b32_e32 v85, v85, v86, vcc
	v_add_f32_e32 v86, 1.0, v87
	v_cmp_gt_f32_e32 vcc, s71, v86
	v_exp_f32_e32 v137, v137
	v_mul_f32_e64 v138, |v109|, s25
	v_cndmask_b32_e64 v87, 0, 32, vcc
	v_ldexp_f32 v86, v86, v87
	v_log_f32_e32 v87, v86
	v_cndmask_b32_e64 v86, 0, v110, s[68:69]
	v_sub_f32_e32 v85, v85, v86
	v_min_f32_e32 v86, 0, v92
	v_mul_f32_e32 v88, 0x3f317217, v87
	v_fma_f32 v88, v87, s20, -v88
	v_fmac_f32_e32 v88, 0x3377d1cf, v87
	v_fmac_f32_e32 v88, 0x3f317217, v87
	v_cmp_lt_f32_e64 s[68:69], |v87|, s21
	v_exp_f32_e32 v138, v138
	v_exp_f32_e32 v140, v140
	v_cndmask_b32_e64 v87, v87, v88, s[68:69]
	v_add_f32_e32 v88, 1.0, v89
	v_cmp_gt_f32_e64 s[68:69], s71, v88
	v_mul_f32_e64 v141, |v139|, s25
	v_exp_f32_e32 v141, v141
	v_cndmask_b32_e64 v89, 0, 32, s[68:69]
	v_ldexp_f32 v88, v88, v89
	v_log_f32_e32 v89, v88
	v_cndmask_b32_e32 v88, 0, v110, vcc
	v_sub_f32_e32 v88, v87, v88
	v_min_f32_e32 v87, 0, v93
	v_mul_f32_e32 v90, 0x3f317217, v89
	v_fma_f32 v90, v89, s20, -v90
	v_fmac_f32_e32 v90, 0x3377d1cf, v89
	v_fmac_f32_e32 v90, 0x3f317217, v89
	v_cmp_lt_f32_e64 vcc, |v89|, s21
	v_mul_f32_e64 v93, |v95|, s25
	v_exp_f32_e32 v93, v93
	v_cndmask_b32_e32 v89, v89, v90, vcc
	v_add_f32_e32 v90, 1.0, v91
	v_cmp_gt_f32_e32 vcc, s71, v90
	v_mul_f32_e64 v144, |v142|, s25
	v_exp_f32_e32 v144, v144
	v_cndmask_b32_e64 v91, 0, 32, vcc
	v_ldexp_f32 v90, v90, v91
	v_log_f32_e32 v91, v90
	v_cndmask_b32_e64 v90, 0, v110, s[68:69]
	v_sub_f32_e32 v89, v89, v90
	v_min_f32_e32 v90, 0, v94
	v_mul_f32_e32 v92, 0x3f317217, v91
	v_fma_f32 v92, v91, s20, -v92
	v_fmac_f32_e32 v92, 0x3377d1cf, v91
	v_fmac_f32_e32 v92, 0x3f317217, v91
	v_cmp_lt_f32_e64 s[68:69], |v91|, s21
	v_mul_f32_e64 v145, |v143|, s25
	v_exp_f32_e32 v145, v145
	v_cndmask_b32_e64 v91, v91, v92, s[68:69]
	v_add_f32_e32 v92, 1.0, v93
	v_cmp_gt_f32_e64 s[68:69], s71, v92
	v_mul_f32_e64 v148, |v146|, s25
	v_exp_f32_e32 v148, v148
	v_cndmask_b32_e64 v93, 0, 32, s[68:69]
	v_ldexp_f32 v92, v92, v93
	v_log_f32_e32 v93, v92
	v_cndmask_b32_e32 v92, 0, v110, vcc
	v_sub_f32_e32 v92, v91, v92
	v_min_f32_e32 v91, 0, v95
	v_mul_f32_e64 v95, |v96|, s25
	v_mul_f32_e32 v94, 0x3f317217, v93
	v_exp_f32_e32 v95, v95
	v_fma_f32 v94, v93, s20, -v94
	v_fmac_f32_e32 v94, 0x3377d1cf, v93
	v_fmac_f32_e32 v94, 0x3f317217, v93
	v_cmp_lt_f32_e64 vcc, |v93|, s21
	v_mul_f32_e64 v149, |v147|, s25
	v_exp_f32_e32 v149, v149
	v_cndmask_b32_e32 v93, v93, v94, vcc
	v_add_f32_e32 v94, 1.0, v95
	v_cmp_gt_f32_e32 vcc, s71, v94
	v_pk_add_f32 v[82:83], v[82:83], v[84:85] neg_lo:[0,1] neg_hi:[0,1]
	v_min_f32_e32 v108, 0, v108
	v_cndmask_b32_e64 v95, 0, 32, vcc
	v_ldexp_f32 v94, v94, v95
; #define GLDS __attribute__((address_space(3)))
; __device__ __forceinline__ float logsig(float z) { return fminf(z, 0.f) - __logf(1.0f + __expf(-fabsf(z))); }
; #define GBAR() asm volatile("s_waitcnt lgkmcnt(0)\n\ts_barrier" ::: "memory")
; #define tid TIDX(wave)
; template <int MODE> __device__ __forceinline__ void chain(int b, int h, int seg, float* __restrict__ SLOC, float* __restrict__ DTOT, const bf16_t* __restrict__ QB, const bf16_t* __restrict__ KB, const bf16_t* __restrict__ VB, bf16_t* __restrict__ OB, const bf16_t* __restrict__ RB, const float* __res ...
;     ...
;             float run0 = 0.f, run1 = 0.f;
; #pragma unroll
;             for (int i = 0; i < 8; ++i) { run0 += logsig(z0[i]) * 0.0625f; run1 += logsig(z1[i]) * 0.0625f; bl0[i] = run0; bl1[i] = run1; }
;             *(GLDS f32x2*)(SEG + wid * 128 + c0) = (f32x2){run0, run1};
;         }
; #pragma unroll
;         for (int j = 0; j < 4; ++j) { const int idx = j * 512 + tid; *(GLDS u32x4*)(L + V_OFF + (idx >> 5) * V_RS + (idx & 31) * 16) = vr[j]; }
;         GBAR();
	v_log_f32_e32 v95, v94
	v_cndmask_b32_e64 v94, 0, v110, s[68:69]
	v_sub_f32_e32 v93, v93, v94
	v_min_f32_e32 v94, 0, v96
	v_mul_f32_e32 v96, 0x3f317217, v95
	v_fma_f32 v96, v95, s20, -v96
	v_fmac_f32_e32 v96, 0x3377d1cf, v95
	v_fmac_f32_e32 v96, 0x3f317217, v95
	v_cmp_lt_f32_e64 s[68:69], |v95|, s21
	v_pk_fma_f32 v[150:151], v[82:83], s[70:71], 0 op_sel_hi:[1,0,0]
	v_pk_add_f32 v[82:83], v[86:87], v[88:89] neg_lo:[0,1] neg_hi:[0,1]
	v_cndmask_b32_e64 v95, v95, v96, s[68:69]
	v_add_f32_e32 v96, 1.0, v136
	v_cmp_gt_f32_e64 s[68:69], s71, v96
	v_pk_fma_f32 v[152:153], v[82:83], s[70:71], v[150:151] op_sel_hi:[1,0,1]
	v_pk_add_f32 v[82:83], v[90:91], v[92:93] neg_lo:[0,1] neg_hi:[0,1]
	v_cndmask_b32_e64 v136, 0, 32, s[68:69]
	v_ldexp_f32 v96, v96, v136
	v_log_f32_e32 v136, v96
	v_cndmask_b32_e32 v96, 0, v110, vcc
	v_sub_f32_e32 v96, v95, v96
	v_min_f32_e32 v95, 0, v97
	v_mul_f32_e32 v97, 0x3f317217, v136
	v_fma_f32 v97, v136, s20, -v97
	v_fmac_f32_e32 v97, 0x3377d1cf, v136
	v_fmac_f32_e32 v97, 0x3f317217, v136
	v_cmp_lt_f32_e64 vcc, |v136|, s21
	v_min_f32_e32 v109, 0, v109
	v_pk_fma_f32 v[154:155], v[82:83], s[70:71], v[152:153] op_sel_hi:[1,0,1]
	v_cndmask_b32_e32 v97, v136, v97, vcc
	v_add_f32_e32 v136, 1.0, v137
	v_cmp_gt_f32_e32 vcc, s71, v136
	v_min_f32_e32 v139, 0, v139
	v_min_f32_e32 v142, 0, v142
	v_cndmask_b32_e64 v137, 0, 32, vcc
	v_ldexp_f32 v136, v136, v137
	v_log_f32_e32 v136, v136
	v_cndmask_b32_e64 v137, 0, v110, s[68:69]
	v_sub_f32_e32 v97, v97, v137
	v_pk_add_f32 v[82:83], v[94:95], v[96:97] neg_lo:[0,1] neg_hi:[0,1]
	v_mul_f32_e32 v137, 0x3f317217, v136
	v_fma_f32 v137, v136, s20, -v137
	v_fmac_f32_e32 v137, 0x3377d1cf, v136
	v_fmac_f32_e32 v137, 0x3f317217, v136
	v_cmp_lt_f32_e64 s[68:69], |v136|, s21
	v_pk_fma_f32 v[156:157], v[82:83], s[70:71], v[154:155] op_sel_hi:[1,0,1]
	v_min_f32_e32 v143, 0, v143
	v_cndmask_b32_e64 v136, v136, v137, s[68:69]
	v_add_f32_e32 v137, 1.0, v138
	v_cmp_gt_f32_e64 s[68:69], s71, v137
	v_min_f32_e32 v146, 0, v146
	v_min_f32_e32 v147, 0, v147
	v_cndmask_b32_e64 v138, 0, 32, s[68:69]
	v_ldexp_f32 v137, v137, v138
	v_log_f32_e32 v137, v137
	v_cndmask_b32_e32 v138, 0, v110, vcc
	v_sub_f32_e32 v136, v136, v138
	v_mul_f32_e32 v138, 0x3f317217, v137
	v_fma_f32 v138, v137, s20, -v138
	v_fmac_f32_e32 v138, 0x3377d1cf, v137
	v_fmac_f32_e32 v138, 0x3f317217, v137
	v_cmp_lt_f32_e64 vcc, |v137|, s21
	s_nop 1
	v_cndmask_b32_e32 v137, v137, v138, vcc
	v_add_f32_e32 v138, 1.0, v140
	v_cmp_gt_f32_e32 vcc, s71, v138
	s_nop 1
	v_cndmask_b32_e64 v140, 0, 32, vcc
	v_ldexp_f32 v138, v138, v140
	v_log_f32_e32 v140, v138
	v_cndmask_b32_e64 v138, 0, v110, s[68:69]
	v_sub_f32_e32 v137, v137, v138
	v_min_f32_e32 v138, 0, v135
	v_mul_f32_e32 v135, 0x3f317217, v140
	v_fma_f32 v135, v140, s20, -v135
	v_fmac_f32_e32 v135, 0x3377d1cf, v140
	v_fmac_f32_e32 v135, 0x3f317217, v140
	v_cmp_lt_f32_e64 s[68:69], |v140|, s21
	v_pk_add_f32 v[82:83], v[108:109], v[136:137] neg_lo:[0,1] neg_hi:[0,1]
	s_nop 0
	v_cndmask_b32_e64 v135, v140, v135, s[68:69]
	v_add_f32_e32 v140, 1.0, v141
	v_cmp_gt_f32_e64 s[68:69], s71, v140
	v_pk_fma_f32 v[136:137], v[82:83], s[70:71], v[156:157] op_sel_hi:[1,0,1]
	s_nop 0
	v_cndmask_b32_e64 v141, 0, 32, s[68:69]
	v_ldexp_f32 v140, v140, v141
	v_log_f32_e32 v141, v140
	v_cndmask_b32_e32 v140, 0, v110, vcc
	v_sub_f32_e32 v140, v135, v140
	v_mul_f32_e32 v135, 0x3f317217, v141
	v_fma_f32 v135, v141, s20, -v135
	v_fmac_f32_e32 v135, 0x3377d1cf, v141
	v_fmac_f32_e32 v135, 0x3f317217, v141
	v_cmp_lt_f32_e64 vcc, |v141|, s21
	s_nop 1
	v_cndmask_b32_e32 v135, v141, v135, vcc
	v_add_f32_e32 v141, 1.0, v144
	v_cmp_gt_f32_e32 vcc, s71, v141
	s_nop 1
	v_cndmask_b32_e64 v144, 0, 32, vcc
	v_ldexp_f32 v141, v141, v144
	v_log_f32_e32 v144, v141
	v_cndmask_b32_e64 v141, 0, v110, s[68:69]
	v_sub_f32_e32 v141, v135, v141
	v_pk_add_f32 v[82:83], v[138:139], v[140:141] neg_lo:[0,1] neg_hi:[0,1]
	v_mul_f32_e32 v135, 0x3f317217, v144
	v_fma_f32 v135, v144, s20, -v135
	v_fmac_f32_e32 v135, 0x3377d1cf, v144
	v_fmac_f32_e32 v135, 0x3f317217, v144
	v_cmp_lt_f32_e64 s[68:69], |v144|, s21
	v_pk_fma_f32 v[138:139], v[82:83], s[70:71], v[136:137] op_sel_hi:[1,0,1]
	s_nop 0
	v_cndmask_b32_e64 v135, v144, v135, s[68:69]
	v_add_f32_e32 v144, 1.0, v145
	v_cmp_gt_f32_e64 s[68:69], s71, v144
	s_nop 1
	v_cndmask_b32_e64 v145, 0, 32, s[68:69]
	v_ldexp_f32 v144, v144, v145
	v_log_f32_e32 v145, v144
	v_cndmask_b32_e32 v144, 0, v110, vcc
	v_sub_f32_e32 v144, v135, v144
	v_mul_f32_e32 v135, 0x3f317217, v145
	v_fma_f32 v135, v145, s20, -v135
	v_fmac_f32_e32 v135, 0x3377d1cf, v145
	v_fmac_f32_e32 v135, 0x3f317217, v145
	v_cmp_lt_f32_e64 vcc, |v145|, s21
	s_nop 1
	v_cndmask_b32_e32 v135, v145, v135, vcc
	v_add_f32_e32 v145, 1.0, v148
	v_cmp_gt_f32_e32 vcc, s71, v145
	s_nop 1
	v_cndmask_b32_e64 v148, 0, 32, vcc
	v_ldexp_f32 v145, v145, v148
	v_log_f32_e32 v148, v145
	v_cndmask_b32_e64 v145, 0, v110, s[68:69]
	v_sub_f32_e32 v145, v135, v145
	v_pk_add_f32 v[82:83], v[142:143], v[144:145] neg_lo:[0,1] neg_hi:[0,1]
	v_mul_f32_e32 v135, 0x3f317217, v148
	v_fma_f32 v135, v148, s20, -v135
	v_fmac_f32_e32 v135, 0x3377d1cf, v148
	v_fmac_f32_e32 v135, 0x3f317217, v148
	v_cmp_lt_f32_e64 s[68:69], |v148|, s21
	v_pk_fma_f32 v[140:141], v[82:83], s[70:71], v[138:139] op_sel_hi:[1,0,1]
	s_nop 0
	v_cndmask_b32_e64 v135, v148, v135, s[68:69]
	v_add_f32_e32 v148, 1.0, v149
	v_cmp_gt_f32_e64 s[68:69], s71, v148
	s_nop 1
	v_cndmask_b32_e64 v149, 0, 32, s[68:69]
	v_ldexp_f32 v148, v148, v149
	v_log_f32_e32 v149, v148
	v_cndmask_b32_e32 v148, 0, v110, vcc
	v_sub_f32_e32 v148, v135, v148
	v_mul_f32_e32 v135, 0x3f317217, v149
	v_fma_f32 v135, v149, s20, -v135
	v_fmac_f32_e32 v135, 0x3377d1cf, v149
	v_fmac_f32_e32 v135, 0x3f317217, v149
	v_cmp_lt_f32_e64 vcc, |v149|, s21
	s_nop 1
	v_cndmask_b32_e32 v135, v149, v135, vcc
	v_cndmask_b32_e64 v149, 0, v110, s[68:69]
	v_sub_f32_e32 v149, v135, v149
	v_pk_add_f32 v[82:83], v[146:147], v[148:149] neg_lo:[0,1] neg_hi:[0,1]
	s_andn2_b64 vcc, exec, s[84:85]
	v_pk_fma_f32 v[142:143], v[82:83], s[70:71], v[140:141] op_sel_hi:[1,0,1]
	ds_write_b64 v125, v[142:143]
	s_waitcnt vmcnt(8)
	ds_write_b128 v129, v[66:69] offset:53248
	ds_write_b128 v130, v[70:73] offset:53248
	ds_write_b128 v131, v[74:77] offset:53248
	ds_write_b128 v132, v[78:81] offset:53248
	s_waitcnt lgkmcnt(0)
	s_barrier
; __device__ __forceinline__ float bflo(unsigned w) { return __uint_as_float(w << 16); }
; __device__ __forceinline__ float bfhi(unsigned w) { return __uint_as_float(w & 0xffff0000u); }
; #define GLDS __attribute__((address_space(3)))
; __device__ __forceinline__ float bflo(unsigned w) { return __uint_as_float(w << 16); }
; __device__ __forceinline__ float bfhi(unsigned w) { return __uint_as_float(w & 0xffff0000u); }
; #define GBAR() asm volatile("s_waitcnt lgkmcnt(0)\n\ts_barrier" ::: "memory")
; template <int MODE> __device__ __forceinline__ void chain(int b, int h, int seg, float* __restrict__ SLOC, float* __restrict__ DTOT, const bf16_t* __restrict__ QB, const bf16_t* __restrict__ KB, const bf16_t* __restrict__ VB, bf16_t* __restrict__ OB, const bf16_t* __restrict__ RB, const float* __res ...
;     ...
;             float pre0 = 0.f, pre1 = 0.f, tot0 = 0.f, tot1 = 0.f;
; #pragma unroll
;             for (int w = 0; w < 8; ++w) { const f32x2 sg = *(const GLDS f32x2*)(SEG + w * 128 + c0); tot0 += sg.x; tot1 += sg.y; if (w < wid) { pre0 += sg.x; pre1 += sg.y; } }
;             unsigned kh0[4], kh1[4];
; #pragma unroll
;             for (int i = 0; i < 8; i += 2) {
;                 float kx0[2], kx1[2];
; #pragma unroll
;                 for (int d = 0; d < 2; ++d) { const int ii = i + d; const float b0 = pre0 + bl0[ii], b1 = pre1 + bl1[ii];
;                     const float qa = bflo(q2[ii]), qb = bfhi(q2[ii]), ka = bflo(k2[ii]), kb = bfhi(k2[ii]);
;                     if (MODE == 1) { *(GLDS unsigned*)(L + QT_OFF + (8 * wid + ii) * QT_RS + c0 * 2) = pk(qa * SCQ * __expf(b0), qb * SCQ * __expf(b1));
;                     *(GLDS unsigned*)(L + KT_OFF + (8 * wid + ii) * QT_RS + c0 * 2) = pk(ka * __expf(-b0), kb * __expf(-b1)); }
;                     kx0[d] = ka * __expf(tot0 - b0); kx1[d] = kb * __expf(tot1 - b1); }
;                 kh0[i >> 1] = pk(kx0[0], kx0[1]); kh1[i >> 1] = pk(kx1[0], kx1[1]);
;             }
;             *(GLDS u32x4*)(L + KH_OFF + c0 * KH_RS + wid * 16) = (u32x4){kh0[0], kh0[1], kh0[2], kh0[3]};
;             *(GLDS u32x4*)(L + KH_OFF + (c0 + 1) * KH_RS + wid * 16) = (u32x4){kh1[0], kh1[1], kh1[2], kh1[3]};
;             if (wid == 0) *(GLDS f32x2*)(EBL + c0) = (f32x2){__expf(tot0), __expf(tot1)};
;             dt0 += tot0; dt1 += tot1;
;         }
;         GBAR();
;         if (n + 1 < 16) GLA_LOAD(row0 + 64);
	ds_read2st64_b64 v[82:85], v126 offset1:1
	ds_read2st64_b64 v[86:89], v126 offset0:2 offset1:3
	ds_read2st64_b64 v[90:93], v126 offset0:4 offset1:5
	ds_read2st64_b64 v[94:97], v126 offset0:6 offset1:7
	s_waitcnt lgkmcnt(3)
	v_pk_add_f32 v[82:83], v[82:83], 0 op_sel_hi:[1,0]
	s_nop 0
	v_cndmask_b32_e64 v108, v83, 0, s[84:85]
	v_cndmask_b32_e64 v109, v82, 0, s[84:85]
	v_pk_add_f32 v[82:83], v[82:83], v[84:85]
	v_add_f32_e32 v85, v85, v108
	v_cndmask_b32_e64 v85, v108, v85, s[38:39]
	s_waitcnt lgkmcnt(2)
	v_pk_add_f32 v[82:83], v[82:83], v[86:87]
	v_add_f32_e32 v87, v87, v85
	v_add_f32_e32 v84, v84, v109
	v_cndmask_b32_e64 v85, v85, v87, s[40:41]
	v_cndmask_b32_e64 v84, v109, v84, s[38:39]
	v_add_f32_e32 v87, v89, v85
	v_add_f32_e32 v86, v86, v84
	v_cndmask_b32_e64 v85, v85, v87, s[42:43]
	v_cndmask_b32_e64 v84, v84, v86, s[40:41]
	s_waitcnt lgkmcnt(1)
	v_add_f32_e32 v87, v91, v85
	v_add_f32_e32 v86, v88, v84
	v_cndmask_b32_e64 v85, v85, v87, s[44:45]
	v_pk_add_f32 v[82:83], v[82:83], v[88:89]
	v_cndmask_b32_e64 v84, v84, v86, s[42:43]
	v_add_f32_e32 v87, v93, v85
	v_pk_add_f32 v[82:83], v[82:83], v[90:91]
	v_add_f32_e32 v86, v90, v84
	v_cndmask_b32_e64 v85, v85, v87, s[46:47]
	v_cndmask_b32_e64 v84, v84, v86, s[44:45]
	v_pk_add_f32 v[82:83], v[82:83], v[92:93]
	s_waitcnt lgkmcnt(0)
	v_add_f32_e32 v87, v95, v85
	v_add_f32_e32 v86, v92, v84
	v_pk_add_f32 v[82:83], v[82:83], v[94:95]
	v_cndmask_b32_e64 v85, v85, v87, s[48:49]
	v_cndmask_b32_e64 v84, v84, v86, s[46:47]
	v_pk_add_f32 v[108:109], v[82:83], v[96:97]
	v_add_f32_e32 v83, v97, v85
	v_add_f32_e32 v86, v94, v84
	v_cndmask_b32_e64 v95, v85, v83, s[50:51]
	v_cndmask_b32_e64 v84, v84, v86, s[48:49]
	v_add_f32_e32 v85, v151, v95
	v_add_f32_e32 v87, v153, v95
	v_add_f32_e32 v82, v96, v84
	v_sub_f32_e32 v85, v109, v85
	v_sub_f32_e32 v87, v109, v87
	v_cndmask_b32_e64 v96, v84, v82, s[50:51]
	v_mul_f32_e32 v85, 0x3fb8aa3b, v85
	v_mul_f32_e32 v87, 0x3fb8aa3b, v87
	v_add_f32_e32 v84, v150, v96
	v_exp_f32_e32 v86, v85
	v_add_f32_e32 v85, v152, v96
	v_exp_f32_e32 v87, v87
	v_sub_f32_e32 v84, v108, v84
	v_sub_f32_e32 v85, v108, v85
	v_mul_f32_e32 v84, 0x3fb8aa3b, v84
	v_mul_f32_e32 v85, 0x3fb8aa3b, v85
	s_waitcnt vmcnt(0)
	v_and_b32_e32 v83, 0xffff0000, v112
	v_and_b32_e32 v82, 0xffff0000, v114
	v_exp_f32_e32 v84, v84
	v_exp_f32_e32 v85, v85
	v_pk_mul_f32 v[86:87], v[86:87], v[82:83]
	v_add_f32_e32 v83, v154, v96
	v_sub_f32_e32 v83, v108, v83
	v_lshlrev_b32_e32 v89, 16, v112
	v_lshlrev_b32_e32 v88, 16, v114
	v_cvt_pk_bf16_f32 v86, v86, v87
	v_add_f32_e32 v87, v155, v95
	v_mul_f32_e32 v83, 0x3fb8aa3b, v83
	v_pk_mul_f32 v[84:85], v[84:85], v[88:89]
	v_exp_f32_e32 v88, v83
	v_sub_f32_e32 v83, v109, v87
	v_mul_f32_e32 v83, 0x3fb8aa3b, v83
	v_exp_f32_e32 v90, v83
	v_add_f32_e32 v83, v156, v96
	v_sub_f32_e32 v83, v108, v83
	v_mul_f32_e32 v83, 0x3fb8aa3b, v83
	v_add_f32_e32 v87, v157, v95
	v_exp_f32_e32 v89, v83
	v_sub_f32_e32 v83, v109, v87
	v_mul_f32_e32 v83, 0x3fb8aa3b, v83
	v_exp_f32_e32 v91, v83
	v_lshlrev_b32_e32 v93, 16, v115
	v_lshlrev_b32_e32 v92, 16, v113
	v_pk_mul_f32 v[88:89], v[88:89], v[92:93]
	v_cvt_pk_bf16_f32 v82, v84, v85
	v_cvt_pk_bf16_f32 v83, v88, v89
	v_add_f32_e32 v89, v137, v95
	v_and_b32_e32 v85, 0xffff0000, v115
	v_and_b32_e32 v84, 0xffff0000, v113
	v_sub_f32_e32 v89, v109, v89
	v_pk_mul_f32 v[84:85], v[90:91], v[84:85]
	v_mul_f32_e32 v89, 0x3fb8aa3b, v89
	v_add_f32_e32 v91, v139, v95
	v_add_f32_e32 v88, v136, v96
	v_exp_f32_e32 v90, v89
	v_add_f32_e32 v89, v138, v96
	v_sub_f32_e32 v91, v109, v91
	v_sub_f32_e32 v88, v108, v88
	v_sub_f32_e32 v89, v108, v89
	v_mul_f32_e32 v91, 0x3fb8aa3b, v91
	v_mul_f32_e32 v88, 0x3fb8aa3b, v88
	v_mul_f32_e32 v89, 0x3fb8aa3b, v89
	v_exp_f32_e32 v91, v91
	v_exp_f32_e32 v88, v88
	v_exp_f32_e32 v89, v89
	v_cvt_pk_bf16_f32 v87, v84, v85
	v_and_b32_e32 v85, 0xffff0000, v117
	v_and_b32_e32 v84, 0xffff0000, v116
	v_lshlrev_b32_e32 v93, 16, v117
	v_lshlrev_b32_e32 v92, 16, v116
	v_pk_mul_f32 v[90:91], v[90:91], v[84:85]
	v_add_f32_e32 v85, v140, v96
	v_pk_mul_f32 v[88:89], v[88:89], v[92:93]
	v_sub_f32_e32 v85, v108, v85
	v_cvt_pk_bf16_f32 v84, v88, v89
	v_add_f32_e32 v89, v141, v95
	v_mul_f32_e32 v85, 0x3fb8aa3b, v85
	v_exp_f32_e32 v92, v85
	v_sub_f32_e32 v85, v109, v89
	v_mul_f32_e32 v85, 0x3fb8aa3b, v85
	v_exp_f32_e32 v94, v85
	v_add_f32_e32 v85, v142, v96
	v_sub_f32_e32 v85, v108, v85
	v_add_f32_e32 v89, v143, v95
	v_mul_f32_e32 v85, 0x3fb8aa3b, v85
	v_exp_f32_e32 v93, v85
	v_sub_f32_e32 v85, v109, v89
	v_mul_f32_e32 v85, 0x3fb8aa3b, v85
	v_exp_f32_e32 v95, v85
	v_cvt_pk_bf16_f32 v88, v90, v91
	v_and_b32_e32 v91, 0xffff0000, v119
	v_and_b32_e32 v90, 0xffff0000, v118
	v_lshlrev_b32_e32 v97, 16, v119
	v_lshlrev_b32_e32 v96, 16, v118
	v_pk_mul_f32 v[92:93], v[92:93], v[96:97]
	v_pk_mul_f32 v[90:91], v[94:95], v[90:91]
	v_cvt_pk_bf16_f32 v85, v92, v93
	v_cvt_pk_bf16_f32 v89, v90, v91
	ds_write_b128 v133, v[82:85] offset:34816
	ds_write_b128 v133, v[86:89] offset:34960
	s_cbranch_vccnz .LBB0_490
	v_mul_f32_e32 v82, 0x3fb8aa3b, v108
	v_mul_f32_e32 v83, 0x3fb8aa3b, v109
	v_exp_f32_e32 v82, v82
	v_exp_f32_e32 v83, v83
	ds_write_b64 v127, v[82:83]
.LBB0_490:
	s_waitcnt lgkmcnt(0)
	s_barrier
	s_cmp_eq_u32 s82, 0x1e0000
	s_cbranch_scc1 .LBB0_487
	v_lshl_add_u64 v[200:201], s[78:79], 0, v[98:99]
	v_add_co_u32_e32 v200, vcc, 0x2801000, v200
	s_nop 1
	v_addc_co_u32_e32 v201, vcc, 0, v201, vcc
	global_load_dword v120, v[200:201], off
	global_load_dword v121, v[200:201], off offset:256
	v_lshl_add_u64 v[204:205], v[106:107], 0, s[82:83]
	v_add_co_u32_e32 v200, vcc, 0x1f620000, v204
	s_nop 1
	v_addc_co_u32_e32 v201, vcc, 0, v205, vcc
	v_add_co_u32_e32 v202, vcc, 0x1f628000, v204
	s_nop 1
	v_addc_co_u32_e32 v203, vcc, 0, v205, vcc
	global_load_dwordx4 v[66:69], v[200:201], off
	global_load_dwordx4 v[70:73], v[202:203], off
	v_add_co_u32_e32 v200, vcc, 0x1f630000, v204
	s_nop 1
	v_addc_co_u32_e32 v201, vcc, 0, v205, vcc
	v_add_co_u32_e32 v202, vcc, 0x1f638000, v204
	s_nop 1
	v_addc_co_u32_e32 v203, vcc, 0, v205, vcc
	global_load_dwordx4 v[74:77], v[200:201], off
	global_load_dwordx4 v[78:81], v[202:203], off
	v_lshl_add_u64 v[200:201], s[80:81], 0, v[98:99]
	v_add_co_u32_e32 v202, vcc, 0x1b510000, v200
	s_nop 1
	v_addc_co_u32_e32 v203, vcc, 0, v201, vcc
	v_add_co_u32_e32 v200, vcc, 0x1b511000, v200
	s_nop 1
	v_addc_co_u32_e32 v201, vcc, 0, v201, vcc
	global_load_dword v114, v[202:203], off
	global_load_dword v112, v[202:203], off offset:1024
	global_load_dword v113, v[202:203], off offset:2048
	global_load_dword v115, v[202:203], off offset:3072
	global_load_dword v116, v[200:201], off
	global_load_dword v117, v[200:201], off offset:1024
	global_load_dword v118, v[200:201], off offset:2048
	global_load_dword v119, v[200:201], off offset:3072
	s_branch .LBB0_487
